# SSD y*silu(z) gate (4 sites of the inter-barrier region): -log2e multiply and +1 packed (v_pk_mul_f32 with negated s[100:101], v_pk_add_f32 1.0), 8 VALU fewer per chunk-loop iteration
# baseline (speedup 1.0000x reference)
.LBB0_360:
	v_add_u32_e32 v156, v106, v107
	ds_read_b128 v[160:163], v156 offset:34816
	ds_read_b128 v[164:167], v156 offset:34880
	ds_read_b128 v[168:171], v156 offset:17408
	ds_read_b128 v[172:175], v156 offset:17472
	ds_read_b128 v[176:179], v138
	ds_read_b128 v[180:183], v138 offset:64
	ds_read_b128 v[184:187], v138 offset:4352
	ds_read_b128 v[188:191], v138 offset:4416
	ds_read_b128 v[192:195], v156 offset:34944
	ds_read_b128 v[202:205], v156 offset:35008
	ds_read_b128 v[206:209], v156 offset:17536
	ds_read_b128 v[210:213], v156 offset:17600
	ds_read_b128 v[214:217], v138 offset:128
	ds_read_b128 v[236:239], v138 offset:192
	ds_read_b128 v[240:243], v138 offset:4480
	ds_read_b128 v[244:247], v138 offset:4544
	s_waitcnt lgkmcnt(11)
	v_mfma_f32_16x16x32_bf16 v[248:251], v[160:163], v[176:179], 0
	v_mfma_f32_16x16x32_bf16 v[176:179], v[168:171], v[176:179], 0
	s_waitcnt lgkmcnt(9)
	v_mfma_f32_16x16x32_bf16 v[160:163], v[160:163], v[184:187], 0
	v_mfma_f32_16x16x32_bf16 v[168:171], v[168:171], v[184:187], 0
	v_mfma_f32_16x16x32_bf16 v[184:187], v[164:167], v[180:183], v[248:251]
	v_mfma_f32_16x16x32_bf16 v[176:179], v[172:175], v[180:183], v[176:179]
	s_waitcnt lgkmcnt(8)
	v_mfma_f32_16x16x32_bf16 v[160:163], v[164:167], v[188:191], v[160:163]
	v_mfma_f32_16x16x32_bf16 v[164:167], v[172:175], v[188:191], v[168:171]
	s_waitcnt lgkmcnt(3)
	v_mfma_f32_16x16x32_bf16 v[168:171], v[192:195], v[214:217], v[184:187]
	v_mfma_f32_16x16x32_bf16 v[172:175], v[206:209], v[214:217], v[176:179]
	s_waitcnt lgkmcnt(1)
	v_mfma_f32_16x16x32_bf16 v[160:163], v[192:195], v[240:243], v[160:163]
	s_nop 0
	ds_read_b128 v[176:179], v139
	ds_read_b64_tr_b16 v[180:181], v140
	ds_read_b64_tr_b16 v[182:183], v140 offset:1088
	ds_read_b64_tr_b16 v[184:185], v140 offset:32
	ds_read_b64_tr_b16 v[186:187], v140 offset:1120
	ds_read_b64_tr_b16 v[188:189], v140 offset:64
	ds_read_b64_tr_b16 v[190:191], v140 offset:1152
	ds_read_b64_tr_b16 v[192:193], v140 offset:96
	ds_read_b64_tr_b16 v[194:195], v140 offset:1184
	v_mfma_f32_16x16x32_bf16 v[164:167], v[206:209], v[240:243], v[164:167]
	s_waitcnt lgkmcnt(9)
	v_mfma_f32_16x16x32_bf16 v[160:163], v[202:205], v[244:247], v[160:163]
	v_mfma_f32_16x16x32_bf16 v[168:171], v[202:205], v[236:239], v[168:171]
	v_mfma_f32_16x16x32_bf16 v[172:175], v[210:213], v[236:239], v[172:175]
	v_mfma_f32_16x16x32_bf16 v[164:167], v[210:213], v[244:247], v[164:167]
	ds_read_b32 v55, v109
	ds_read_b128 v[202:205], v127
	s_waitcnt lgkmcnt(0)
	v_pk_add_f32 v[198:199], v[54:55], v[202:203] op_sel:[1,0] op_sel_hi:[1,1] neg_lo:[0,1] neg_hi:[0,1]
	v_pk_add_f32 v[222:223], v[54:55], v[204:205] op_sel:[1,0] op_sel_hi:[1,1] neg_lo:[0,1] neg_hi:[0,1]
	v_pk_mul_f32 v[198:199], v[198:199], s[100:101]
	v_pk_mul_f32 v[222:223], v[222:223], s[100:101]
	v_exp_f32_e32 v198, v198
	v_exp_f32_e32 v199, v199
	v_exp_f32_e32 v222, v222
	v_exp_f32_e32 v223, v223
	v_pk_mul_f32 v[198:199], v[172:173], v[198:199]
	v_pk_mul_f32 v[222:223], v[174:175], v[222:223]
	v_cndmask_b32_e64 v198, v198, 0, s[42:43]
	v_cndmask_b32_e64 v199, 0, v199, s[44:45]
	v_cndmask_b32_e64 v222, v222, 0, s[46:47]
	v_cndmask_b32_e64 v223, v223, 0, s[48:49]
	v_cvt_pk_bf16_f32 v172, v198, v199
	v_cvt_pk_bf16_f32 v173, v222, v223
	ds_write_b64 v144, v[172:173]
	ds_read_b32 v89, v110
	ds_read_b128 v[172:175], v127
	v_mul_f32_e32 v55, 0x3fb8aa3b, v55
	v_exp_f32_e32 v154, v55
	s_waitcnt lgkmcnt(0)
	v_mul_f32_e32 v55, 0x3fb8aa3b, v89
	v_pk_add_f32 v[198:199], v[88:89], v[172:173] op_sel:[1,0] op_sel_hi:[1,1] neg_lo:[0,1] neg_hi:[0,1]
	v_pk_add_f32 v[222:223], v[88:89], v[174:175] op_sel:[1,0] op_sel_hi:[1,1] neg_lo:[0,1] neg_hi:[0,1]
	v_pk_mul_f32 v[198:199], v[198:199], s[100:101]
	v_pk_mul_f32 v[222:223], v[222:223], s[100:101]
	v_exp_f32_e32 v198, v198
	v_exp_f32_e32 v199, v199
	v_exp_f32_e32 v222, v222
	v_exp_f32_e32 v223, v223
	v_exp_f32_e32 v206, v55
	v_pk_mul_f32 v[198:199], v[164:165], v[198:199]
	v_pk_mul_f32 v[222:223], v[166:167], v[222:223]
	v_cndmask_b32_e64 v198, v198, 0, s[50:51]
	v_cndmask_b32_e64 v199, 0, v199, s[52:53]
	v_cndmask_b32_e64 v222, v222, 0, s[54:55]
	v_cndmask_b32_e64 v223, v223, 0, s[56:57]
	v_cvt_pk_bf16_f32 v164, v198, v199
	v_cvt_pk_bf16_f32 v165, v222, v223
	ds_write_b64 v145, v[164:165]
	v_mul_f32_e32 v54, 0x3fb8aa3b, v54
	v_exp_f32_e32 v54, v54
	ds_read_b64_tr_b16 v[164:165], v140 offset:8704
	ds_read_b64_tr_b16 v[166:167], v140 offset:9792
	v_add_u32_e32 v159, v108, v111
	ds_read_b128 v[172:175], v159
	v_pk_mul_f32 v[50:51], v[50:51], v[54:55] op_sel_hi:[1,0]
	v_pk_mul_f32 v[48:49], v[48:49], v[54:55] op_sel_hi:[1,0]
	v_pk_mul_f32 v[42:43], v[42:43], v[54:55] op_sel_hi:[1,0]
	v_pk_mul_f32 v[40:41], v[40:41], v[54:55] op_sel_hi:[1,0]
	v_pk_mul_f32 v[46:47], v[46:47], v[54:55] op_sel_hi:[1,0]
	v_pk_mul_f32 v[44:45], v[44:45], v[54:55] op_sel_hi:[1,0]
	v_pk_mul_f32 v[38:39], v[38:39], v[54:55] op_sel_hi:[1,0]
	v_pk_mul_f32 v[36:37], v[36:37], v[54:55] op_sel_hi:[1,0]
	v_mfma_f32_16x16x32_bf16 v[48:51], v[180:183], v[176:179], v[48:51]
	v_add_u32_e32 v54, v112, v113
	v_mfma_f32_16x16x32_bf16 v[40:43], v[184:187], v[176:179], v[40:43]
	v_mfma_f32_16x16x32_bf16 v[44:47], v[188:191], v[176:179], v[44:47]
	v_mfma_f32_16x16x32_bf16 v[36:39], v[192:195], v[176:179], v[36:39]
	ds_read_b64_tr_b16 v[176:177], v140 offset:8736
	ds_read_b64_tr_b16 v[178:179], v140 offset:9824
	s_waitcnt lgkmcnt(2)
	v_mfma_f32_16x16x32_bf16 v[48:51], v[164:167], v[172:175], v[48:51]
	ds_read_b64_tr_b16 v[164:165], v140 offset:8768
	ds_read_b64_tr_b16 v[166:167], v140 offset:9856
	ds_read_b64_tr_b16 v[180:181], v140 offset:8800
	ds_read_b64_tr_b16 v[182:183], v140 offset:9888
	s_waitcnt lgkmcnt(0)
	s_barrier
	s_waitcnt lgkmcnt(2)
	v_mfma_f32_16x16x32_bf16 v[40:43], v[176:179], v[172:175], v[40:43]
	ds_read_b128 v[176:179], v54
	ds_read_b128 v[184:187], v150
	v_add_u32_e32 v54, v112, v111
	s_waitcnt lgkmcnt(3)
	v_mfma_f32_16x16x32_bf16 v[44:47], v[164:167], v[172:175], v[44:47]
	ds_read_b128 v[164:167], v150 offset:2304
	ds_read_b128 v[188:191], v150 offset:64
	ds_read_b128 v[192:195], v54
	ds_read_b128 v[202:205], v150 offset:2368
	s_waitcnt lgkmcnt(6)
	v_mfma_f32_16x16x32_bf16 v[36:39], v[180:183], v[172:175], v[36:39]
	v_mul_f32_e64 v170, v170, v154
	v_mul_f32_e64 v171, v171, v154
	v_pk_mul_f32 v[168:169], v[168:169], v[154:155] op_sel_hi:[1,0]
	v_pk_mul_f32 v[162:163], v[162:163], v[206:207] op_sel_hi:[1,0]
	v_pk_mul_f32 v[160:161], v[160:161], v[206:207] op_sel_hi:[1,0]
	s_waitcnt lgkmcnt(4)
	v_mfma_f32_16x16x32_bf16 v[168:171], v[176:179], v[184:187], v[168:171]
	v_cvt_pk_bf16_f32 v54, v48, v49
	v_cvt_pk_bf16_f32 v55, v50, v51
	v_cvt_pk_bf16_f32 v172, v40, v41
	v_cvt_pk_bf16_f32 v173, v42, v43
	v_add_u32_e32 v157, 0x8800, v151
	s_waitcnt lgkmcnt(3)
	v_mfma_f32_16x16x32_bf16 v[160:163], v[176:179], v[164:167], v[160:163]
	ds_write2_b64 v157, v[54:55], v[172:173] offset1:4
	v_cvt_pk_bf16_f32 v54, v44, v45
	v_cvt_pk_bf16_f32 v55, v46, v47
	s_waitcnt lgkmcnt(2)
	v_mfma_f32_16x16x32_bf16 v[164:167], v[192:195], v[188:191], v[168:171]
	v_cmp_lt_i32_e32 vcc, v225, v220
	v_lshl_add_u64 v[92:93], v[86:87], 0, v[92:93]
	s_nop 0
	v_cvt_pk_bf16_f32 v168, v36, v37
	v_cvt_pk_bf16_f32 v169, v38, v39
	ds_write2_b64 v157, v[54:55], v[168:169] offset0:8 offset1:12
	v_cndmask_b32_e32 v54, v218, v225, vcc
	v_lshlrev_b32_e32 v153, 2, v54
	s_waitcnt vmcnt(9)
	v_lshlrev_b32_e32 v54, 16, v52
	v_and_b32_e32 v55, 0xffff0000, v52
	v_pk_mul_f32 v[170:171], v[54:55], s[100:101] neg_lo:[0,1] neg_hi:[0,1]
	v_exp_f32_e32 v170, v170
	v_exp_f32_e32 v171, v171
	ds_read_b64 v[168:169], v128
	v_pk_add_f32 v[170:171], v[170:171], 1.0 op_sel_hi:[1,0]
	v_rcp_f32_e32 v170, v170
	v_rcp_f32_e32 v171, v171
	s_waitcnt lgkmcnt(0)
	v_lshlrev_b32_e32 v172, 16, v168
	v_and_b32_e32 v173, 0xffff0000, v168
	v_pk_fma_f32 v[164:165], v[0:1], v[172:173], v[164:165]
	v_pk_mul_f32 v[54:55], v[170:171], v[54:55]
	v_lshlrev_b32_e32 v52, 16, v53
	v_pk_mul_f32 v[164:165], v[54:55], v[164:165]
	v_and_b32_e32 v53, 0xffff0000, v53
	v_pk_mul_f32 v[170:171], v[52:53], s[100:101] neg_lo:[0,1] neg_hi:[0,1]
	v_exp_f32_e32 v170, v170
	v_exp_f32_e32 v171, v171
	v_lshlrev_b32_e32 v168, 16, v169
	v_pk_add_f32 v[170:171], v[170:171], 1.0 op_sel_hi:[1,0]
	v_rcp_f32_e32 v170, v170
	v_rcp_f32_e32 v171, v171
	v_and_b32_e32 v169, 0xffff0000, v169
	v_pk_fma_f32 v[166:167], v[0:1], v[168:169], v[166:167]
	v_pk_mul_f32 v[54:55], v[164:165], v[164:165]
	v_pk_mul_f32 v[52:53], v[170:171], v[52:53]
	v_add_f32_e32 v54, v54, v55
	v_pk_mul_f32 v[166:167], v[52:53], v[166:167]
	v_cmp_lt_i32_e32 vcc, v226, v220
	v_pk_mul_f32 v[52:53], v[166:167], v[166:167]
	s_nop 0
	v_add_f32_e32 v52, v52, v54
	v_add_f32_e32 v89, v53, v52
	ds_bpermute_b32 v168, v153, v89
	v_cndmask_b32_e32 v154, v218, v226, vcc
	v_lshlrev_b32_e32 v154, 2, v154
	v_mfma_f32_16x16x32_bf16 v[52:55], v[192:195], v[202:205], v[160:163]
	s_waitcnt lgkmcnt(0)
	v_add_f32_e32 v89, v89, v168
	s_nop 0
	ds_bpermute_b32 v160, v154, v89
	v_cvt_pk_bf16_f32 v162, v164, v165
	v_cvt_pk_bf16_f32 v163, v166, v167
	global_store_dwordx2 v[92:93], v[162:163], off
	s_and_saveexec_b64 s[0:1], s[58:59]
	s_cbranch_execz .LBB0_362
	s_waitcnt lgkmcnt(0)
	v_add_f32_e32 v89, v89, v160
	ds_write_b32 v114, v89
.LBB0_362:
	s_or_b64 exec, exec, s[0:1]
	s_waitcnt vmcnt(9)
	v_lshlrev_b32_e32 v162, 16, v84
	v_and_b32_e32 v163, 0xffff0000, v84
	v_pk_mul_f32 v[164:165], v[162:163], s[100:101] neg_lo:[0,1] neg_hi:[0,1]
	v_exp_f32_e32 v164, v164
	v_exp_f32_e32 v165, v165
	ds_read_b64 v[92:93], v129
	v_pk_add_f32 v[164:165], v[164:165], 1.0 op_sel_hi:[1,0]
	v_rcp_f32_e32 v164, v164
	v_rcp_f32_e32 v165, v165
	s_waitcnt lgkmcnt(0)
	v_lshlrev_b32_e32 v160, 16, v92
	v_and_b32_e32 v161, 0xffff0000, v92
	v_pk_fma_f32 v[52:53], v[0:1], v[160:161], v[52:53]
	v_lshlrev_b32_e32 v84, 16, v85
	v_and_b32_e32 v85, 0xffff0000, v85
	v_pk_mul_f32 v[160:161], v[164:165], v[162:163]
	v_pk_mul_f32 v[162:163], v[84:85], s[100:101] neg_lo:[0,1] neg_hi:[0,1]
	v_exp_f32_e32 v162, v162
	v_exp_f32_e32 v163, v163
	v_lshlrev_b32_e32 v92, 16, v93
	v_pk_add_f32 v[162:163], v[162:163], 1.0 op_sel_hi:[1,0]
	v_rcp_f32_e32 v162, v162
	v_rcp_f32_e32 v163, v163
	v_and_b32_e32 v93, 0xffff0000, v93
	v_pk_mul_f32 v[52:53], v[160:161], v[52:53]
	v_pk_fma_f32 v[54:55], v[0:1], v[92:93], v[54:55]
	v_pk_mul_f32 v[160:161], v[52:53], v[52:53]
	v_cvt_pk_bf16_f32 v52, v52, v53
	v_add_f32_e32 v89, v160, v161
	v_pk_mul_f32 v[84:85], v[162:163], v[84:85]
	s_nop 0
	v_pk_mul_f32 v[54:55], v[84:85], v[54:55]
	s_nop 0
	v_pk_mul_f32 v[84:85], v[54:55], v[54:55]
	v_cvt_pk_bf16_f32 v53, v54, v55
	v_add_f32_e32 v84, v84, v89
	v_add_f32_e32 v84, v85, v84
	v_lshl_add_u64 v[54:55], v[86:87], 0, v[90:91]
	global_store_dwordx2 v[54:55], v[52:53], off
	ds_bpermute_b32 v52, v153, v84
	s_waitcnt lgkmcnt(0)
	v_add_f32_e32 v52, v84, v52
	ds_bpermute_b32 v53, v154, v52
	s_and_saveexec_b64 s[0:1], s[58:59]
	s_cbranch_execz .LBB0_364
	s_waitcnt lgkmcnt(0)
	v_add_f32_e32 v52, v52, v53
	ds_write_b32 v114, v52 offset:64
